# prep phase: setup items redistributed over workgroups so none carries two long items plus short ones
# speedup vs baseline: 1.0013x; 1.0013x over previous
; __global__ void __launch_bounds__(512, 2) k_mega(P p) {
;     ...
;     for (int it = N_TR_ITEMS + blockIdx.x; it < N_PREP; it += gridDim.x) prep_item(*pk, it, smem);
.LBB0_5:
	s_or_b64 exec, exec, s[4:5]
	s_add_i32 s3, s2, 0xb50
	s_cmpk_gt_i32 s3, 0xed7
	s_cbranch_scc1 .LBB0_56
	s_mov_b32 s22, 0
	s_mov_b32 s24, 0
	s_mov_b32 s26, 0
	s_mov_b32 s36, 0x54442d18
	s_mov_b32 s42, 0x6dc9c883
	s_mov_b32 s44, 0x33145c00
	s_mov_b32 s46, 0x252049c0
	s_mov_b32 s48, 0x9037ab78
	s_mov_b32 s50, 0x46cc5e42
	s_mov_b32 s52, 0xa17f65f6
	s_mov_b32 s54, 0x19f4ec90
	s_mov_b32 s56, 0x16c16967
	s_mov_b32 s58, 0x55555555
	s_mov_b32 s60, 0xb42fdfa7
	s_mov_b32 s62, 0xf9a43bb8
	s_mov_b32 s64, 0x796cde01
	s_mov_b32 s66, 0x19e83e5c
	s_mov_b32 s68, 0x11110bb3
	s_mov_b32 s33, 0x3fb8aa3b
	s_mov_b32 s82, 0xc2ce8ed0
	s_mov_b32 s21, 0
	s_mov_b32 s84, 0x42b17218
	s_mov_b32 s23, 0x41d00000
	s_mov_b32 s25, 0x7b000000
	s_movk_i32 s85, 0xff80
	s_mov_b32 s27, 0x7ff00000
	v_mov_b32_e32 v34, 0
	s_mov_b32 s31, 0x3ff921fb
	s_mov_b32 s37, 0xbff921fb
	s_mov_b32 s39, 0x3c91a626
	s_mov_b32 s40, 0x33145c07
	s_mov_b32 s43, 0x3fe45f30
	s_mov_b32 s45, 0xbc91a626
	s_mov_b32 s47, 0xb97b839a
	s_mov_b32 s49, 0x3e21eeb6
	s_mov_b32 s51, 0xbda907db
	s_mov_b32 s53, 0xbe927e4f
	s_mov_b32 s55, 0x3efa01a0
	s_mov_b32 s57, 0xbf56c16c
	s_mov_b32 s59, 0x3fa55555
	s_mov_b32 s61, 0xbe5ae600
	s_mov_b32 s63, 0x3de5e0b2
	s_mov_b32 s65, 0x3ec71de3
	s_mov_b32 s67, 0xbf2a01a0
	s_mov_b32 s69, 0x3f811111
	s_mov_b32 s71, 0xbfc55555
	s_brev_b32 s86, 1
	s_movk_i32 s87, 0x1f8
	s_movk_i32 s88, 0x800
	s_movk_i32 s89, 0x2410
	s_movk_i32 s90, 0x2000
	s_mov_b64 s[72:73], 0x20000
	s_movk_i32 s91, 0x1ff
	s_mov_b32 s92, 0xbfb8aa3b
	s_mov_b32 s93, 0x42ce8ed0
	s_mov_b32 s94, 0xc2b17218
	s_mov_b64 s[74:75], 0x800
	s_movk_i32 s95, 0x5ff
	s_movk_i32 s96, 0x6000
	s_mov_b64 s[76:77], 0xba000
	s_movk_i32 s97, 0x80
	s_mov_b64 s[78:79], 0xc0000
	v_mov_b32_e32 v1, 0x7f800000
	v_mov_b32_e32 v45, 0x40100000
	v_mov_b32_e32 v66, 0x3ff00000
	v_mov_b32_e32 v67, 0x7ff80000
	v_mov_b32_e32 v68, 0x1800000
	s_mov_b32 s98, 0
	s_branch .LBB0_9

; __global__ void __launch_bounds__(512, 2) k_mega(P p) {
;     ...
;     for (int it = N_TR_ITEMS + blockIdx.x; it < N_PREP; it += gridDim.x) prep_item(*pk, it, smem);
.LBB0_8:
	s_cmpk_lg_i32 s34, 0x100
	s_cbranch_scc1 .Lpi_orig
	s_add_i32 s98, s98, 1
	s_cmpk_lt_i32 s2, 0x88
	s_cbranch_scc0 .Lpi_hi
	s_cmp_eq_u32 s98, 1
	s_cbranch_scc0 .LBB0_56
	s_addk_i32 s3, 0x100
	s_branch .LBB0_9
.Lpi_hi:
	s_cmp_eq_u32 s98, 1
	s_cbranch_scc0 .Lpi_hi2
	s_add_i32 s3, s2, 0xc50
	s_branch .Lpi_chk
.Lpi_hi2:
	s_addk_i32 s3, 0x78
	s_branch .Lpi_chk

; __global__ void __launch_bounds__(512, 2) k_mega(P p) {
;     ...
;     for (int it = N_TR_ITEMS + blockIdx.x; it < N_PREP; it += gridDim.x) prep_item(*pk, it, smem);
.Lpi_chk:
	s_cmpk_gt_i32 s3, 0xed7
	s_cbranch_scc1 .LBB0_56

; __global__ void __launch_bounds__(512, 2) k_mega(P p) {
	.amdhsa_kernel _Z6k_mega1P
		.amdhsa_group_segment_fixed_size 0
		.amdhsa_private_segment_fixed_size 0
		.amdhsa_kernarg_size 792
		.amdhsa_user_sgpr_count 2
		.amdhsa_user_sgpr_dispatch_ptr 0
		.amdhsa_user_sgpr_queue_ptr 0
		.amdhsa_user_sgpr_kernarg_segment_ptr 1
		.amdhsa_user_sgpr_dispatch_id 0
		.amdhsa_user_sgpr_kernarg_preload_length 0
		.amdhsa_user_sgpr_kernarg_preload_offset 0
		.amdhsa_user_sgpr_private_segment_size 0
		.amdhsa_uses_dynamic_stack 0
		.amdhsa_enable_private_segment 0
		.amdhsa_system_sgpr_workgroup_id_x 1
		.amdhsa_system_sgpr_workgroup_id_y 0
		.amdhsa_system_sgpr_workgroup_id_z 0
		.amdhsa_system_sgpr_workgroup_info 0
		.amdhsa_system_vgpr_workitem_id 2
		.amdhsa_next_free_vgpr 256
		.amdhsa_next_free_sgpr 99
		.amdhsa_accum_offset 256
		.amdhsa_reserve_vcc 1
		.amdhsa_float_round_mode_32 0
		.amdhsa_float_round_mode_16_64 0
		.amdhsa_float_denorm_mode_32 3
		.amdhsa_float_denorm_mode_16_64 3
		.amdhsa_dx10_clamp 1
		.amdhsa_ieee_mode 1
		.amdhsa_fp16_overflow 0
		.amdhsa_tg_split 0
		.amdhsa_exception_fp_ieee_invalid_op 0
		.amdhsa_exception_fp_denorm_src 0
		.amdhsa_exception_fp_ieee_div_zero 0
		.amdhsa_exception_fp_ieee_overflow 0
		.amdhsa_exception_fp_ieee_underflow 0
		.amdhsa_exception_fp_ieee_inexact 0
		.amdhsa_exception_int_div_zero 0
	.end_amdhsa_kernel

; __global__ void __launch_bounds__(512, 2) k_mega(P p) {
amdhsa.kernels:
  - .agpr_count:     0
    .args:
      - .offset:         0
        .size:           536
        .value_kind:     by_value
      - .offset:         536
        .size:           4
        .value_kind:     hidden_block_count_x
      - .offset:         540
        .size:           4
        .value_kind:     hidden_block_count_y
      - .offset:         544
        .size:           4
        .value_kind:     hidden_block_count_z
      - .offset:         548
        .size:           2
        .value_kind:     hidden_group_size_x
      - .offset:         550
        .size:           2
        .value_kind:     hidden_group_size_y
      - .offset:         552
        .size:           2
        .value_kind:     hidden_group_size_z
      - .offset:         554
        .size:           2
        .value_kind:     hidden_remainder_x
      - .offset:         556
        .size:           2
        .value_kind:     hidden_remainder_y
      - .offset:         558
        .size:           2
        .value_kind:     hidden_remainder_z
      - .offset:         576
        .size:           8
        .value_kind:     hidden_global_offset_x
      - .offset:         584
        .size:           8
        .value_kind:     hidden_global_offset_y
      - .offset:         592
        .size:           8
        .value_kind:     hidden_global_offset_z
      - .offset:         600
        .size:           2
        .value_kind:     hidden_grid_dims
      - .offset:         624
        .size:           8
        .value_kind:     hidden_multigrid_sync_arg
      - .offset:         656
        .size:           4
        .value_kind:     hidden_dynamic_lds_size
    .group_segment_fixed_size: 0
    .kernarg_segment_align: 8
    .kernarg_segment_size: 792
    .language:       OpenCL C
    .language_version:
      - 2
      - 0
    .max_flat_workgroup_size: 512
    .name:           _Z6k_mega1P
    .private_segment_fixed_size: 0
    .sgpr_count:     105
    .sgpr_spill_count: 44
    .symbol:         _Z6k_mega1P.kd
    .uniform_work_group_size: 1
    .uses_dynamic_stack: false
    .vgpr_count:     256
    .vgpr_spill_count: 0
    .wavefront_size: 64
